# speedup vs baseline: 1.0010x; 1.0010x over previous
; #define LAS __attribute__((address_space(3)))
; __device__ __forceinline__ void phase_attn(const Params& p, int l, LAS unsigned char* lds, int bid, int G, int tid) {
;     ...
;                     const int qb = 2 * qh + blk; int ks0 = 16 * qb - 8; ks0 = ks0 < 0 ? 0 : ks0; ks0 = ks0 > 32 ? 32 : ks0;
;                     f32x4 St[2];
; #pragma unroll
;                     for (int nb = 0; nb < 2; ++nb) { f32x4 a0 = {0.f, 0.f, 0.f, 0.f};
; #pragma unroll
;                         for (int ks = 0; ks < 4; ++ks) { const bf16x8 kf = *(const LAS bf16x8*)(Kt + (ks0 + nb * 16 + fr) * 272 + (ks * 32 + g * 8) * 2);
;                             a0 = __builtin_amdgcn_mfma_f32_16x16x32_bf16(kf, Qf[blk][ks], a0, 0, 0, 0); }
;                         St[nb] = a0; }
;                     const int qc = qb * 16 + fr; int cs = qc - 8; cs = cs < 0 ? 0 : cs; cs = cs > 48 ? 48 : cs;
;                     float mt = -INFINITY;
; #pragma unroll
;                     for (int nb = 0; nb < 2; ++nb)
; #pragma unroll
;                         for (int j = 0; j < 4; ++j) { const int kc = ks0 + nb * 16 + g * 4 + j; const bool ok = (kc >= cs) && (kc < cs + 16);
;                             int dc = kc - qc; dc = dc < -15 ? -15 : dc; dc = dc > 15 ? 15 : dc;
;                             const float sv = ok ? St[nb][j] + rp[dc + 15] : -INFINITY; St[nb][j] = sv; mt = fmaxf(mt, sv); }
;                     mt = fmaxf(mt, __shfl_xor(mt, 16)); mt = fmaxf(mt, __shfl_xor(mt, 32));
;                     const float mnew = fmaxf(mrun[blk], mt), alpha = __expf(mrun[blk] - mnew);
;                     float psum = 0.f;
; #pragma unroll
;                     for (int nb = 0; nb < 2; ++nb)
; #pragma unroll
;                         for (int j = 0; j < 4; ++j) { const float pe = __expf(St[nb][j] - mnew); St[nb][j] = pe; psum += pe; }
;                     lrun[blk] = lrun[blk] * alpha + psum; mrun[blk] = mnew;
;                     u32x4 pv; pv.x = pk2(St[0][0], St[0][1]); pv.y = pk2(St[0][2], St[0][3]); pv.z = pk2(St[1][0], St[1][1]); pv.w = pk2(St[1][2], St[1][3]);
;                     const bf16x8 Pf = __builtin_bit_cast(bf16x8, pv);
; #pragma unroll
;                     for (int db = 0; db < 8; ++db) { const LAS unsigned char* vp = Vt + (db * 16 + fr) * 144 + (ks0 + g * 4) * 2;
;                         const u32x2 lo = *(const LAS u32x2*)(vp), hi = *(const LAS u32x2*)(vp + 32);
.LBB0_247:
	s_movk_i32 s45, 0x1400
	s_add_i32 s4, s18, s94
	v_cmp_ge_u32_e32 vcc, s4, v135
	v_cmp_lt_u32_e64 s[4:5], s4, v137
	s_and_b64 s[40:41], vcc, s[4:5]
	s_waitcnt lgkmcnt(0)
	s_barrier
	s_and_saveexec_b64 s[4:5], s[40:41]
	s_cbranch_execz .LBB0_244
	ds_read_b128 v[116:119], v209
	ds_read_b128 v[120:123], v209 offset:64
	ds_read_b128 v[234:237], v209 offset:128
	ds_read_b128 v[238:241], v209 offset:192
	ds_read_b128 v[242:245], v209 offset:4352
	ds_read_b128 v[212:215], v209 offset:4416
	ds_read_b128 v[246:249], v209 offset:4480
	s_waitcnt lgkmcnt(6)
	v_mfma_f32_16x16x32_bf16 v[116:119], v[116:119], v[4:7], 0
	s_waitcnt lgkmcnt(5)
	v_mfma_f32_16x16x32_bf16 v[116:119], v[120:123], v[8:11], v[116:119]
	s_waitcnt lgkmcnt(4)
	v_mfma_f32_16x16x32_bf16 v[116:119], v[234:237], v[12:15], v[116:119]
	ds_read_b128 v[234:237], v209 offset:4544
	s_waitcnt lgkmcnt(4)
	v_mfma_f32_16x16x32_bf16 v[116:119], v[238:241], v[16:19], v[116:119]
	s_waitcnt lgkmcnt(3)
	v_mfma_f32_16x16x32_bf16 v[120:123], v[242:245], v[4:7], 0
	s_waitcnt lgkmcnt(2)
	v_mfma_f32_16x16x32_bf16 v[120:123], v[212:215], v[8:11], v[120:123]
	s_waitcnt lgkmcnt(1)
	v_mfma_f32_16x16x32_bf16 v[120:123], v[246:249], v[12:15], v[120:123]
	s_waitcnt lgkmcnt(0)
	v_mfma_f32_16x16x32_bf16 v[120:123], v[234:237], v[16:19], v[120:123]
	v_add_u32_e32 v234, v1, v174
	v_add_u32_e32 v235, v1, v175
	v_add_u32_e32 v236, v1, v176
	v_add_u32_e32 v237, v1, v177
	v_add_u32_e32 v238, v1, v195
	v_add_u32_e32 v239, v1, v196
	v_add_u32_e32 v240, v1, v197
	v_add_u32_e32 v241, v1, v198
	ds_read_b32 v234, v234 offset:36892
	ds_read_b32 v235, v235 offset:36892
	ds_read_b32 v236, v236 offset:36892
	ds_read_b32 v237, v237 offset:36892
	ds_read_b32 v238, v238 offset:36892
	ds_read_b32 v239, v239 offset:36892
	ds_read_b32 v240, v240 offset:36892
	ds_read_b32 v241, v241 offset:36892
	v_mov_b32_e32 v248, 0xff800000
	s_waitcnt lgkmcnt(0)
	v_add_f32_e32 v234, v116, v234
	v_add_f32_e32 v235, v117, v235
	v_add_f32_e32 v236, v118, v236
	v_add_f32_e32 v237, v119, v237
	v_add_f32_e32 v238, v120, v238
	v_add_f32_e32 v239, v121, v239
	v_add_f32_e32 v240, v122, v240
	v_add_f32_e32 v241, v123, v241
	v_cndmask_b32_e64 v214, v248, v234, s[8:9]
	v_cndmask_b32_e64 v215, v248, v235, s[10:11]
	v_cndmask_b32_e64 v224, v248, v236, s[12:13]
	v_cndmask_b32_e64 v116, v248, v237, s[24:25]
	v_cndmask_b32_e64 v118, v248, v238, s[26:27]
	v_cndmask_b32_e64 v117, v248, v239, s[28:29]
	v_cndmask_b32_e64 v120, v248, v240, s[30:31]
	v_cndmask_b32_e64 v119, v248, v241, s[34:35]
	v_mov_b32_e32 v213, 0xff800000
	v_max3_f32 v121, v214, v213, v215
	v_max3_f32 v121, v121, v224, v116
	v_max3_f32 v121, v121, v118, v117
	v_max3_f32 v121, v121, v120, v119
	ds_bpermute_b32 v122, v169, v121
	v_add_u32_e32 v220, v167, v144
	s_waitcnt lgkmcnt(0)
	v_max_f32_e32 v122, v122, v122
	v_max_f32_e32 v121, v121, v122
	ds_bpermute_b32 v122, v170, v121
	s_waitcnt lgkmcnt(0)
	v_max3_f32 v212, v142, v121, v122
	v_sub_f32_e32 v116, v116, v212
	v_sub_f32_e32 v122, v214, v212
	v_mul_f32_e32 v116, 0x3fb8aa3b, v116
	v_mul_f32_e32 v122, 0x3fb8aa3b, v122
	v_exp_f32_e32 v225, v116
	v_sub_f32_e32 v116, v118, v212
	v_exp_f32_e32 v214, v122
	v_sub_f32_e32 v122, v215, v212
	v_mul_f32_e32 v116, 0x3fb8aa3b, v116
	v_mul_f32_e32 v122, 0x3fb8aa3b, v122
	v_exp_f32_e32 v226, v116
	v_sub_f32_e32 v116, v117, v212
	v_sub_f32_e32 v121, v142, v212
	v_exp_f32_e32 v215, v122
	v_sub_f32_e32 v122, v224, v212
	v_mul_f32_e32 v116, 0x3fb8aa3b, v116
	v_mul_f32_e32 v121, 0x3fb8aa3b, v121
	v_mul_f32_e32 v122, 0x3fb8aa3b, v122
	v_exp_f32_e32 v227, v116
	v_sub_f32_e32 v116, v120, v212
	v_add_u32_e32 v120, 0x4000, v220
	v_exp_f32_e32 v224, v122
	v_exp_f32_e32 v142, v121
	ds_read2_b64 v[120:123], v120 offset0:128 offset1:132
	v_mul_f32_e32 v116, 0x3fb8aa3b, v116
	v_exp_f32_e32 v228, v116
	v_sub_f32_e32 v116, v119, v212
	v_mul_f32_e32 v116, 0x3fb8aa3b, v116
	v_pk_mul_f32 v[54:55], v[54:55], v[142:143] op_sel_hi:[1,0]
	v_pk_mul_f32 v[52:53], v[52:53], v[142:143] op_sel_hi:[1,0]
	v_exp_f32_e32 v229, v116
	v_cvt_pk_bf16_f32 v116, v214, v215
	v_cvt_pk_bf16_f32 v117, v224, v225
	v_cvt_pk_bf16_f32 v118, v226, v227
	v_cvt_pk_bf16_f32 v119, v228, v229
	v_pk_mul_f32 v[58:59], v[58:59], v[142:143] op_sel_hi:[1,0]
	s_waitcnt lgkmcnt(0)
; #define LAS __attribute__((address_space(3)))
; __device__ __forceinline__ void phase_attn(const Params& p, int l, LAS unsigned char* lds, int bid, int G, int tid) {
;     ...
;                     const int qb = 2 * qh + blk; int ks0 = 16 * qb - 8; ks0 = ks0 < 0 ? 0 : ks0; ks0 = ks0 > 32 ? 32 : ks0;
;                     f32x4 St[2];
; #pragma unroll
;                     for (int nb = 0; nb < 2; ++nb) { f32x4 a0 = {0.f, 0.f, 0.f, 0.f};
; #pragma unroll
;                         for (int ks = 0; ks < 4; ++ks) { const bf16x8 kf = *(const LAS bf16x8*)(Kt + (ks0 + nb * 16 + fr) * 272 + (ks * 32 + g * 8) * 2);
;                             a0 = __builtin_amdgcn_mfma_f32_16x16x32_bf16(kf, Qf[blk][ks], a0, 0, 0, 0); }
;                         St[nb] = a0; }
;                     const int qc = qb * 16 + fr; int cs = qc - 8; cs = cs < 0 ? 0 : cs; cs = cs > 48 ? 48 : cs;
;                     float mt = -INFINITY;
; #pragma unroll
;                     for (int nb = 0; nb < 2; ++nb)
; #pragma unroll
;                         for (int j = 0; j < 4; ++j) { const int kc = ks0 + nb * 16 + g * 4 + j; const bool ok = (kc >= cs) && (kc < cs + 16);
;                             int dc = kc - qc; dc = dc < -15 ? -15 : dc; dc = dc > 15 ? 15 : dc;
;                             const float sv = ok ? St[nb][j] + rp[dc + 15] : -INFINITY; St[nb][j] = sv; mt = fmaxf(mt, sv); }
;                     mt = fmaxf(mt, __shfl_xor(mt, 16)); mt = fmaxf(mt, __shfl_xor(mt, 32));
;                     const float mnew = fmaxf(mrun[blk], mt), alpha = __expf(mrun[blk] - mnew);
;                     float psum = 0.f;
; #pragma unroll
;                     for (int nb = 0; nb < 2; ++nb)
; #pragma unroll
;                         for (int j = 0; j < 4; ++j) { const float pe = __expf(St[nb][j] - mnew); St[nb][j] = pe; psum += pe; }
;                     lrun[blk] = lrun[blk] * alpha + psum; mrun[blk] = mnew;
;                     u32x4 pv; pv.x = pk2(St[0][0], St[0][1]); pv.y = pk2(St[0][2], St[0][3]); pv.z = pk2(St[1][0], St[1][1]); pv.w = pk2(St[1][2], St[1][3]);
;                     const bf16x8 Pf = __builtin_bit_cast(bf16x8, pv);
; #pragma unroll
;                     for (int db = 0; db < 8; ++db) { const LAS unsigned char* vp = Vt + (db * 16 + fr) * 144 + (ks0 + g * 4) * 2;
;                         const u32x2 lo = *(const LAS u32x2*)(vp), hi = *(const LAS u32x2*)(vp + 32);
	v_mfma_f32_16x16x32_bf16 v[52:55], v[120:123], v[116:119], v[52:55]
	v_add_u32_e32 v120, 0x4800, v220
	ds_read2_b64 v[120:123], v120 offset0:160 offset1:164
	v_pk_mul_f32 v[56:57], v[56:57], v[142:143] op_sel_hi:[1,0]
	v_pk_mul_f32 v[62:63], v[62:63], v[142:143] op_sel_hi:[1,0]
	v_pk_mul_f32 v[60:61], v[60:61], v[142:143] op_sel_hi:[1,0]
	s_waitcnt lgkmcnt(0)
	v_mfma_f32_16x16x32_bf16 v[56:59], v[120:123], v[116:119], v[56:59]
	v_add_u32_e32 v120, 0x5000, v220
	ds_read2_b64 v[120:123], v120 offset0:192 offset1:196
	v_pk_mul_f32 v[66:67], v[66:67], v[142:143] op_sel_hi:[1,0]
	s_waitcnt lgkmcnt(0)
	v_mfma_f32_16x16x32_bf16 v[60:63], v[120:123], v[116:119], v[60:63]
	v_add_u32_e32 v120, 0x5800, v220
	ds_read2_b64 v[120:123], v120 offset0:224 offset1:228
	v_pk_mul_f32 v[64:65], v[64:65], v[142:143] op_sel_hi:[1,0]
	v_pk_mul_f32 v[74:75], v[74:75], v[142:143] op_sel_hi:[1,0]
	v_pk_mul_f32 v[72:73], v[72:73], v[142:143] op_sel_hi:[1,0]
	s_waitcnt lgkmcnt(0)
	v_mfma_f32_16x16x32_bf16 v[64:67], v[120:123], v[116:119], v[64:67]
	v_add_u32_e32 v120, 0x6800, v220
	ds_read2_b64 v[120:123], v120 offset1:4
	v_pk_mul_f32 v[82:83], v[82:83], v[142:143] op_sel_hi:[1,0]
	s_waitcnt lgkmcnt(0)
	v_mfma_f32_16x16x32_bf16 v[72:75], v[120:123], v[116:119], v[72:75]
	v_add_u32_e32 v120, 0x7000, v220
	ds_read2_b64 v[120:123], v120 offset0:32 offset1:36
	v_pk_mul_f32 v[80:81], v[80:81], v[142:143] op_sel_hi:[1,0]
	v_pk_mul_f32 v[70:71], v[70:71], v[142:143] op_sel_hi:[1,0]
	v_pk_mul_f32 v[68:69], v[68:69], v[142:143] op_sel_hi:[1,0]
	s_waitcnt lgkmcnt(0)
	v_mfma_f32_16x16x32_bf16 v[80:83], v[120:123], v[116:119], v[80:83]
	v_add_u32_e32 v120, 0x7800, v220
	ds_read2_b64 v[120:123], v120 offset0:64 offset1:68
	v_pk_mul_f32 v[78:79], v[78:79], v[142:143] op_sel_hi:[1,0]
	s_waitcnt lgkmcnt(0)
	v_mfma_f32_16x16x32_bf16 v[68:71], v[120:123], v[116:119], v[68:71]
	v_add_u32_e32 v120, 0x8000, v220
	ds_read2_b64 v[120:123], v120 offset0:96 offset1:100
	v_pk_mul_f32 v[76:77], v[76:77], v[142:143] op_sel_hi:[1,0]
	v_add_u32_e32 v220, v166, v153
	ds_read_b128 v[230:233], v220 offset:4416
	s_waitcnt lgkmcnt(1)
	v_mfma_f32_16x16x32_bf16 v[76:79], v[120:123], v[116:119], v[76:79]
	ds_read_b128 v[116:119], v220
	ds_read_b128 v[120:123], v220 offset:64
	ds_read_b128 v[234:237], v220 offset:128
	ds_read_b128 v[238:241], v220 offset:192
	s_waitcnt lgkmcnt(3)
	v_mfma_f32_16x16x32_bf16 v[116:119], v[116:119], v[20:23], 0
	s_waitcnt lgkmcnt(2)
	v_mfma_f32_16x16x32_bf16 v[116:119], v[120:123], v[24:27], v[116:119]
	s_waitcnt lgkmcnt(1)
	v_mfma_f32_16x16x32_bf16 v[116:119], v[234:237], v[28:31], v[116:119]
	s_waitcnt lgkmcnt(0)
	v_mfma_f32_16x16x32_bf16 v[120:123], v[238:241], v[32:35], v[116:119]
	s_nop 4
	ds_read_b128 v[116:119], v220 offset:4352
	s_waitcnt lgkmcnt(0)
	v_mfma_f32_16x16x32_bf16 v[116:119], v[116:119], v[20:23], 0
	v_mfma_f32_16x16x32_bf16 v[116:119], v[230:233], v[24:27], v[116:119]
	ds_read_b128 v[230:233], v220 offset:4480
	s_waitcnt lgkmcnt(0)
	v_mfma_f32_16x16x32_bf16 v[116:119], v[230:233], v[28:31], v[116:119]
	ds_read_b128 v[230:233], v220 offset:4544
	s_waitcnt lgkmcnt(0)
	v_mfma_f32_16x16x32_bf16 v[116:119], v[230:233], v[32:35], v[116:119]
	v_add_u32_e32 v234, v1, v199
	v_add_u32_e32 v235, v1, v200
	v_add_u32_e32 v236, v1, v201
	v_add_u32_e32 v237, v1, v202
	v_add_u32_e32 v238, v1, v203
	v_add_u32_e32 v239, v1, v204
	v_add_u32_e32 v240, v1, v205
	v_add_u32_e32 v241, v1, v206
	ds_read_b32 v234, v234 offset:36892
	ds_read_b32 v235, v235 offset:36892
	ds_read_b32 v236, v236 offset:36892
	ds_read_b32 v237, v237 offset:36892
	ds_read_b32 v238, v238 offset:36892
	ds_read_b32 v239, v239 offset:36892
	ds_read_b32 v240, v240 offset:36892
	ds_read_b32 v241, v241 offset:36892
	v_mov_b32_e32 v248, 0xff800000
	s_waitcnt lgkmcnt(0)
	v_add_f32_e32 v234, v120, v234
	v_add_f32_e32 v235, v121, v235
	v_add_f32_e32 v236, v122, v236
	v_add_f32_e32 v237, v123, v237
	v_add_f32_e32 v238, v116, v238
	v_add_f32_e32 v239, v117, v239
	v_add_f32_e32 v240, v118, v240
	v_add_f32_e32 v241, v119, v241
	v_cndmask_b32_e64 v230, v248, v234, s[36:37]
	v_cndmask_b32_e64 v213, v248, v235, s[48:49]
	v_cndmask_b32_e64 v231, v248, v236, s[74:75]
	v_cndmask_b32_e64 v120, v248, v237, s[76:77]
	v_cndmask_b32_e64 v123, v248, v238, s[78:79]
	v_cndmask_b32_e64 v122, v248, v239, s[82:83]
	v_cndmask_b32_e64 v117, v248, v240, s[84:85]
	v_cndmask_b32_e64 v116, v248, v241, s[86:87]
	s_mov_b64 s[40:41], exec
	s_branch .LBB0_243
